# barrier: arrival-time L1 invalidate only for workgroups that are not their XCD's last arriver (the last one invalidates once, after its write-back)
# baseline (speedup 1.0000x reference)
; DI unsigned xb_ld(unsigned* p) { return __hip_atomic_load(p, __ATOMIC_RELAXED, __HIP_MEMORY_SCOPE_AGENT); }
; DI unsigned xb_add(unsigned* p, unsigned v) { return __hip_atomic_fetch_add(p, v, __ATOMIC_RELAXED, __HIP_MEMORY_SCOPE_AGENT); }
; #define XB_SPIN(cond, bar) do { unsigned _sp = 0; while (cond) { __builtin_amdgcn_s_sleep(1); \
;     if ((++_sp & 255u) == 0u) { if (xb_ld(&(bar)[XB_TMO])) break; if (_sp > XB_SPIN_CAP) { atomicAdd(&(bar)[XB_TMO], 1u); break; } } } } while (0)
; DI void xcd_barrier(const XcdBarrier& b) {
;     ...
;     const unsigned old = xb_add(&bar[XB_XSUB(b.x)], 1u);
;     const unsigned gen = old / nloc;
;     if (old + 1u == (gen + 1u) * nloc) {
;       __builtin_amdgcn_fence(__ATOMIC_RELEASE, "agent");
;       asm volatile("s_waitcnt vmcnt(0)" ::: "memory");
;       const unsigned og = xb_add(&bar[XB_TOP], 1u);
;       const unsigned tg = og / nx;
;       if (og + 1u == (tg + 1u) * nx) xb_add(&bar[XB_TOPGEN], 1u);
;       else XB_SPIN(xb_ld(&bar[XB_TOPGEN]) == tg, bar);
;       __builtin_amdgcn_fence(__ATOMIC_ACQUIRE, "agent");
;       xb_add(&bar[XB_XGEN(b.x)], 1u);
;       asm volatile("s_waitcnt vmcnt(0)" ::: "memory");
;     } else {
;       XB_SPIN(xb_ld(&bar[XB_XGEN(b.x)]) == gen, bar);
.LBB0_184:
	s_or_b64 exec, exec, s[14:15]
	v_cvt_f32_u32_e32 v4, v2
	s_waitcnt vmcnt(0)
	v_readfirstlane_b32 s0, v3
	v_sub_u32_e32 v3, 0, v2
	v_rcp_iflag_f32_e32 v4, v4
	v_add_u32_e32 v5, s0, v1
	v_mul_f32_e32 v4, 0x4f7ffffe, v4
	v_cvt_u32_f32_e32 v4, v4
	v_mul_lo_u32 v1, v3, v4
	v_mul_hi_u32 v1, v4, v1
	v_add_u32_e32 v1, v4, v1
	v_mul_hi_u32 v1, v5, v1
	v_mul_lo_u32 v3, v1, v2
	v_sub_u32_e32 v3, v5, v3
	v_add_u32_e32 v4, 1, v1
	v_cmp_ge_u32_e32 vcc, v3, v2
	s_nop 1
	v_cndmask_b32_e32 v1, v1, v4, vcc
	v_sub_u32_e32 v4, v3, v2
	v_cndmask_b32_e32 v3, v3, v4, vcc
	v_add_u32_e32 v4, 1, v1
	v_cmp_ge_u32_e32 vcc, v3, v2
	v_add_u32_e32 v3, 1, v5
	s_nop 0
	v_cndmask_b32_e32 v1, v1, v4, vcc
	v_mul_lo_u32 v4, v2, v1
	v_add_u32_e32 v2, v4, v2
	v_cmp_ne_u32_e32 vcc, v3, v2
	s_and_saveexec_b64 s[0:1], vcc
	s_xor_b64 s[12:13], exec, s[0:1]
	s_cbranch_execz .LBB0_198
	buffer_inv sc1
	s_waitcnt lgkmcnt(0)
	v_mov_b32_e32 v0, 0x2000
	global_load_dword v0, v0, s[10:11] offset:1024 sc1
	s_add_u32 s20, s10, 0x2400
	s_addc_u32 s21, s11, 0
	s_waitcnt vmcnt(0)
	v_cmp_eq_u32_e32 vcc, v0, v1
	s_and_saveexec_b64 s[14:15], vcc
	s_cbranch_execz .LBB0_197
	s_add_u32 s16, s86, 0xe7c1200
	s_addc_u32 s17, s87, 0
	s_mov_b32 s0, 1
	s_mov_b64 s[30:31], 0
	v_mov_b32_e32 v0, 0
	s_branch .LBB0_188

; DI unsigned xb_ld(unsigned* p) { return __hip_atomic_load(p, __ATOMIC_RELAXED, __HIP_MEMORY_SCOPE_AGENT); }
; DI unsigned xb_add(unsigned* p, unsigned v) { return __hip_atomic_fetch_add(p, v, __ATOMIC_RELAXED, __HIP_MEMORY_SCOPE_AGENT); }
; #define XB_SPIN(cond, bar) do { unsigned _sp = 0; while (cond) { __builtin_amdgcn_s_sleep(1); \
;     if ((++_sp & 255u) == 0u) { if (xb_ld(&(bar)[XB_TMO])) break; if (_sp > XB_SPIN_CAP) { atomicAdd(&(bar)[XB_TMO], 1u); break; } } } } while (0)
; DI void xcd_barrier(const XcdBarrier& b) {
;     ...
;     const unsigned old = xb_add(&bar[XB_XSUB(b.x)], 1u);
;     const unsigned gen = old / nloc;
;     if (old + 1u == (gen + 1u) * nloc) {
;       __builtin_amdgcn_fence(__ATOMIC_RELEASE, "agent");
;       asm volatile("s_waitcnt vmcnt(0)" ::: "memory");
;       const unsigned og = xb_add(&bar[XB_TOP], 1u);
;       const unsigned tg = og / nx;
;       if (og + 1u == (tg + 1u) * nx) xb_add(&bar[XB_TOPGEN], 1u);
;       else XB_SPIN(xb_ld(&bar[XB_TOPGEN]) == tg, bar);
;       __builtin_amdgcn_fence(__ATOMIC_ACQUIRE, "agent");
;       xb_add(&bar[XB_XGEN(b.x)], 1u);
;       asm volatile("s_waitcnt vmcnt(0)" ::: "memory");
;     } else {
;       XB_SPIN(xb_ld(&bar[XB_XGEN(b.x)]) == gen, bar);
.LBB0_249:
	s_or_b64 exec, exec, s[12:13]
	v_cvt_f32_u32_e32 v4, v2
	s_waitcnt vmcnt(0)
	v_readfirstlane_b32 s0, v3
	v_sub_u32_e32 v3, 0, v2
	v_rcp_iflag_f32_e32 v4, v4
	v_add_u32_e32 v5, s0, v1
	v_mul_f32_e32 v4, 0x4f7ffffe, v4
	v_cvt_u32_f32_e32 v4, v4
	v_mul_lo_u32 v1, v3, v4
	v_mul_hi_u32 v1, v4, v1
	v_add_u32_e32 v1, v4, v1
	v_mul_hi_u32 v1, v5, v1
	v_mul_lo_u32 v3, v1, v2
	v_sub_u32_e32 v3, v5, v3
	v_add_u32_e32 v4, 1, v1
	v_cmp_ge_u32_e32 vcc, v3, v2
	s_nop 1
	v_cndmask_b32_e32 v1, v1, v4, vcc
	v_sub_u32_e32 v4, v3, v2
	v_cndmask_b32_e32 v3, v3, v4, vcc
	v_add_u32_e32 v4, 1, v1
	v_cmp_ge_u32_e32 vcc, v3, v2
	v_add_u32_e32 v3, 1, v5
	s_nop 0
	v_cndmask_b32_e32 v1, v1, v4, vcc
	v_mul_lo_u32 v4, v2, v1
	v_add_u32_e32 v2, v4, v2
	v_cmp_ne_u32_e32 vcc, v3, v2
	s_and_saveexec_b64 s[0:1], vcc
	s_xor_b64 s[10:11], exec, s[0:1]
	s_cbranch_execz .LBB0_263
	buffer_inv sc1
	s_waitcnt lgkmcnt(0)
	v_mov_b32_e32 v0, 0x2000
	global_load_dword v0, v0, s[8:9] offset:1024 sc1
	s_add_u32 s16, s8, 0x2400
	s_addc_u32 s17, s9, 0
	s_waitcnt vmcnt(0)
	v_cmp_eq_u32_e32 vcc, v0, v1
	s_and_saveexec_b64 s[12:13], vcc
	s_cbranch_execz .LBB0_262
	s_add_u32 s14, s86, 0xe7c1200
	s_addc_u32 s15, s87, 0
	s_mov_b32 s0, 1
	s_mov_b64 s[20:21], 0
	v_mov_b32_e32 v0, 0
	s_branch .LBB0_253

; DI unsigned xb_ld(unsigned* p) { return __hip_atomic_load(p, __ATOMIC_RELAXED, __HIP_MEMORY_SCOPE_AGENT); }
; DI unsigned xb_add(unsigned* p, unsigned v) { return __hip_atomic_fetch_add(p, v, __ATOMIC_RELAXED, __HIP_MEMORY_SCOPE_AGENT); }
; #define XB_SPIN(cond, bar) do { unsigned _sp = 0; while (cond) { __builtin_amdgcn_s_sleep(1); \
;     if ((++_sp & 255u) == 0u) { if (xb_ld(&(bar)[XB_TMO])) break; if (_sp > XB_SPIN_CAP) { atomicAdd(&(bar)[XB_TMO], 1u); break; } } } } while (0)
; DI void xcd_barrier(const XcdBarrier& b) {
;     ...
;     const unsigned old = xb_add(&bar[XB_XSUB(b.x)], 1u);
;     const unsigned gen = old / nloc;
;     if (old + 1u == (gen + 1u) * nloc) {
;       __builtin_amdgcn_fence(__ATOMIC_RELEASE, "agent");
;       asm volatile("s_waitcnt vmcnt(0)" ::: "memory");
;       const unsigned og = xb_add(&bar[XB_TOP], 1u);
;       const unsigned tg = og / nx;
;       if (og + 1u == (tg + 1u) * nx) xb_add(&bar[XB_TOPGEN], 1u);
;       else XB_SPIN(xb_ld(&bar[XB_TOPGEN]) == tg, bar);
;       __builtin_amdgcn_fence(__ATOMIC_ACQUIRE, "agent");
;       xb_add(&bar[XB_XGEN(b.x)], 1u);
;       asm volatile("s_waitcnt vmcnt(0)" ::: "memory");
;     } else {
;       XB_SPIN(xb_ld(&bar[XB_XGEN(b.x)]) == gen, bar);
.LBB0_490:
	s_or_b64 exec, exec, s[12:13]
	v_cvt_f32_u32_e32 v4, v2
	s_waitcnt vmcnt(0)
	v_readfirstlane_b32 s0, v3
	v_sub_u32_e32 v3, 0, v2
	v_rcp_iflag_f32_e32 v4, v4
	v_add_u32_e32 v5, s0, v1
	v_mul_f32_e32 v4, 0x4f7ffffe, v4
	v_cvt_u32_f32_e32 v4, v4
	v_mul_lo_u32 v1, v3, v4
	v_mul_hi_u32 v1, v4, v1
	v_add_u32_e32 v1, v4, v1
	v_mul_hi_u32 v1, v5, v1
	v_mul_lo_u32 v3, v1, v2
	v_sub_u32_e32 v3, v5, v3
	v_add_u32_e32 v4, 1, v1
	v_cmp_ge_u32_e32 vcc, v3, v2
	s_nop 1
	v_cndmask_b32_e32 v1, v1, v4, vcc
	v_sub_u32_e32 v4, v3, v2
	v_cndmask_b32_e32 v3, v3, v4, vcc
	v_add_u32_e32 v4, 1, v1
	v_cmp_ge_u32_e32 vcc, v3, v2
	v_add_u32_e32 v3, 1, v5
	s_nop 0
	v_cndmask_b32_e32 v1, v1, v4, vcc
	v_mul_lo_u32 v4, v2, v1
	v_add_u32_e32 v2, v4, v2
	v_cmp_ne_u32_e32 vcc, v3, v2
	s_and_saveexec_b64 s[0:1], vcc
	s_xor_b64 s[10:11], exec, s[0:1]
	s_cbranch_execz .LBB0_504
	buffer_inv sc1
	s_waitcnt lgkmcnt(0)
	v_mov_b32_e32 v0, 0x2000
	global_load_dword v0, v0, s[8:9] offset:1024 sc1
	s_add_u32 s16, s8, 0x2400
	s_addc_u32 s17, s9, 0
	s_waitcnt vmcnt(0)
	v_cmp_eq_u32_e32 vcc, v0, v1
	s_and_saveexec_b64 s[12:13], vcc
	s_cbranch_execz .LBB0_503
	s_add_u32 s14, s86, 0xe7c1200
	s_addc_u32 s15, s87, 0
	s_mov_b32 s0, 1
	s_mov_b64 s[30:31], 0
	v_mov_b32_e32 v0, 0
	s_branch .LBB0_494

; DI unsigned xb_ld(unsigned* p) { return __hip_atomic_load(p, __ATOMIC_RELAXED, __HIP_MEMORY_SCOPE_AGENT); }
; DI unsigned xb_add(unsigned* p, unsigned v) { return __hip_atomic_fetch_add(p, v, __ATOMIC_RELAXED, __HIP_MEMORY_SCOPE_AGENT); }
; #define XB_SPIN(cond, bar) do { unsigned _sp = 0; while (cond) { __builtin_amdgcn_s_sleep(1); \
;     if ((++_sp & 255u) == 0u) { if (xb_ld(&(bar)[XB_TMO])) break; if (_sp > XB_SPIN_CAP) { atomicAdd(&(bar)[XB_TMO], 1u); break; } } } } while (0)
; DI void xcd_barrier(const XcdBarrier& b) {
;     ...
;     const unsigned old = xb_add(&bar[XB_XSUB(b.x)], 1u);
;     const unsigned gen = old / nloc;
;     if (old + 1u == (gen + 1u) * nloc) {
;       __builtin_amdgcn_fence(__ATOMIC_RELEASE, "agent");
;       asm volatile("s_waitcnt vmcnt(0)" ::: "memory");
;       const unsigned og = xb_add(&bar[XB_TOP], 1u);
;       const unsigned tg = og / nx;
;       if (og + 1u == (tg + 1u) * nx) xb_add(&bar[XB_TOPGEN], 1u);
;       else XB_SPIN(xb_ld(&bar[XB_TOPGEN]) == tg, bar);
;       __builtin_amdgcn_fence(__ATOMIC_ACQUIRE, "agent");
;       xb_add(&bar[XB_XGEN(b.x)], 1u);
;       asm volatile("s_waitcnt vmcnt(0)" ::: "memory");
;     } else {
;       XB_SPIN(xb_ld(&bar[XB_XGEN(b.x)]) == gen, bar);
.LBB0_829:
	s_or_b64 exec, exec, s[12:13]
	v_cvt_f32_u32_e32 v4, v2
	s_waitcnt vmcnt(0)
	v_readfirstlane_b32 s0, v3
	v_sub_u32_e32 v3, 0, v2
	v_rcp_iflag_f32_e32 v4, v4
	v_add_u32_e32 v5, s0, v1
	v_mul_f32_e32 v4, 0x4f7ffffe, v4
	v_cvt_u32_f32_e32 v4, v4
	v_mul_lo_u32 v1, v3, v4
	v_mul_hi_u32 v1, v4, v1
	v_add_u32_e32 v1, v4, v1
	v_mul_hi_u32 v1, v5, v1
	v_mul_lo_u32 v3, v1, v2
	v_sub_u32_e32 v3, v5, v3
	v_add_u32_e32 v4, 1, v1
	v_cmp_ge_u32_e32 vcc, v3, v2
	s_nop 1
	v_cndmask_b32_e32 v1, v1, v4, vcc
	v_sub_u32_e32 v4, v3, v2
	v_cndmask_b32_e32 v3, v3, v4, vcc
	v_add_u32_e32 v4, 1, v1
	v_cmp_ge_u32_e32 vcc, v3, v2
	v_add_u32_e32 v3, 1, v5
	s_nop 0
	v_cndmask_b32_e32 v1, v1, v4, vcc
	v_mul_lo_u32 v4, v2, v1
	v_add_u32_e32 v2, v4, v2
	v_cmp_ne_u32_e32 vcc, v3, v2
	s_and_saveexec_b64 s[0:1], vcc
	s_xor_b64 s[10:11], exec, s[0:1]
	s_cbranch_execz .LBB0_843
	buffer_inv sc1
	s_waitcnt lgkmcnt(0)
	v_mov_b32_e32 v0, 0x2000
	global_load_dword v0, v0, s[8:9] offset:1024 sc1
	s_add_u32 s16, s8, 0x2400
	s_addc_u32 s17, s9, 0
	s_waitcnt vmcnt(0)
	v_cmp_eq_u32_e32 vcc, v0, v1
	s_and_saveexec_b64 s[12:13], vcc
	s_cbranch_execz .LBB0_842
	s_add_u32 s14, s86, 0xe7c1200
	s_addc_u32 s15, s87, 0
	s_mov_b32 s0, 1
	s_mov_b64 s[26:27], 0
	v_mov_b32_e32 v0, 0
	s_branch .LBB0_833

; DI unsigned xb_ld(unsigned* p) { return __hip_atomic_load(p, __ATOMIC_RELAXED, __HIP_MEMORY_SCOPE_AGENT); }
; DI unsigned xb_add(unsigned* p, unsigned v) { return __hip_atomic_fetch_add(p, v, __ATOMIC_RELAXED, __HIP_MEMORY_SCOPE_AGENT); }
; #define XB_SPIN(cond, bar) do { unsigned _sp = 0; while (cond) { __builtin_amdgcn_s_sleep(1); \
;     if ((++_sp & 255u) == 0u) { if (xb_ld(&(bar)[XB_TMO])) break; if (_sp > XB_SPIN_CAP) { atomicAdd(&(bar)[XB_TMO], 1u); break; } } } } while (0)
; DI void xcd_barrier(const XcdBarrier& b) {
;     ...
;     const unsigned old = xb_add(&bar[XB_XSUB(b.x)], 1u);
;     const unsigned gen = old / nloc;
;     if (old + 1u == (gen + 1u) * nloc) {
;       __builtin_amdgcn_fence(__ATOMIC_RELEASE, "agent");
;       asm volatile("s_waitcnt vmcnt(0)" ::: "memory");
;       const unsigned og = xb_add(&bar[XB_TOP], 1u);
;       const unsigned tg = og / nx;
;       if (og + 1u == (tg + 1u) * nx) xb_add(&bar[XB_TOPGEN], 1u);
;       else XB_SPIN(xb_ld(&bar[XB_TOPGEN]) == tg, bar);
;       __builtin_amdgcn_fence(__ATOMIC_ACQUIRE, "agent");
;       xb_add(&bar[XB_XGEN(b.x)], 1u);
;       asm volatile("s_waitcnt vmcnt(0)" ::: "memory");
;     } else {
;       XB_SPIN(xb_ld(&bar[XB_XGEN(b.x)]) == gen, bar);
.LBB0_941:
	s_or_b64 exec, exec, s[12:13]
	v_cvt_f32_u32_e32 v4, v2
	s_waitcnt vmcnt(0)
	v_readfirstlane_b32 s0, v3
	v_sub_u32_e32 v3, 0, v2
	v_rcp_iflag_f32_e32 v4, v4
	v_add_u32_e32 v5, s0, v1
	v_mul_f32_e32 v4, 0x4f7ffffe, v4
	v_cvt_u32_f32_e32 v4, v4
	v_mul_lo_u32 v1, v3, v4
	v_mul_hi_u32 v1, v4, v1
	v_add_u32_e32 v1, v4, v1
	v_mul_hi_u32 v1, v5, v1
	v_mul_lo_u32 v3, v1, v2
	v_sub_u32_e32 v3, v5, v3
	v_add_u32_e32 v4, 1, v1
	v_cmp_ge_u32_e32 vcc, v3, v2
	s_nop 1
	v_cndmask_b32_e32 v1, v1, v4, vcc
	v_sub_u32_e32 v4, v3, v2
	v_cndmask_b32_e32 v3, v3, v4, vcc
	v_add_u32_e32 v4, 1, v1
	v_cmp_ge_u32_e32 vcc, v3, v2
	v_add_u32_e32 v3, 1, v5
	s_nop 0
	v_cndmask_b32_e32 v1, v1, v4, vcc
	v_mul_lo_u32 v4, v2, v1
	v_add_u32_e32 v2, v4, v2
	v_cmp_ne_u32_e32 vcc, v3, v2
	s_and_saveexec_b64 s[0:1], vcc
	s_xor_b64 s[10:11], exec, s[0:1]
	s_cbranch_execz .LBB0_955
	buffer_inv sc1
	s_waitcnt lgkmcnt(0)
	v_mov_b32_e32 v0, 0x2000
	global_load_dword v0, v0, s[8:9] offset:1024 sc1
	s_add_u32 s16, s8, 0x2400
	s_addc_u32 s17, s9, 0
	s_waitcnt vmcnt(0)
	v_cmp_eq_u32_e32 vcc, v0, v1
	s_and_saveexec_b64 s[12:13], vcc
	s_cbranch_execz .LBB0_954
	s_add_u32 s14, s86, 0xe7c1200
	s_addc_u32 s15, s87, 0
	s_mov_b32 s0, 1
	s_mov_b64 s[24:25], 0
	v_mov_b32_e32 v0, 0
	s_branch .LBB0_945

; DI unsigned xb_ld(unsigned* p) { return __hip_atomic_load(p, __ATOMIC_RELAXED, __HIP_MEMORY_SCOPE_AGENT); }
; DI unsigned xb_add(unsigned* p, unsigned v) { return __hip_atomic_fetch_add(p, v, __ATOMIC_RELAXED, __HIP_MEMORY_SCOPE_AGENT); }
; #define XB_SPIN(cond, bar) do { unsigned _sp = 0; while (cond) { __builtin_amdgcn_s_sleep(1); \
;     if ((++_sp & 255u) == 0u) { if (xb_ld(&(bar)[XB_TMO])) break; if (_sp > XB_SPIN_CAP) { atomicAdd(&(bar)[XB_TMO], 1u); break; } } } } while (0)
; DI void xcd_barrier(const XcdBarrier& b) {
;     ...
;     const unsigned old = xb_add(&bar[XB_XSUB(b.x)], 1u);
;     const unsigned gen = old / nloc;
;     if (old + 1u == (gen + 1u) * nloc) {
;       __builtin_amdgcn_fence(__ATOMIC_RELEASE, "agent");
;       asm volatile("s_waitcnt vmcnt(0)" ::: "memory");
;       const unsigned og = xb_add(&bar[XB_TOP], 1u);
;       const unsigned tg = og / nx;
;       if (og + 1u == (tg + 1u) * nx) xb_add(&bar[XB_TOPGEN], 1u);
;       else XB_SPIN(xb_ld(&bar[XB_TOPGEN]) == tg, bar);
;       __builtin_amdgcn_fence(__ATOMIC_ACQUIRE, "agent");
;       xb_add(&bar[XB_XGEN(b.x)], 1u);
;       asm volatile("s_waitcnt vmcnt(0)" ::: "memory");
;     } else {
;       XB_SPIN(xb_ld(&bar[XB_XGEN(b.x)]) == gen, bar);
.LBB0_1067:
	s_or_b64 exec, exec, s[22:23]
	v_cvt_f32_u32_e32 v4, v2
	s_waitcnt vmcnt(0)
	v_readfirstlane_b32 s0, v3
	v_sub_u32_e32 v3, 0, v2
	v_rcp_iflag_f32_e32 v4, v4
	v_add_u32_e32 v5, s0, v1
	v_mul_f32_e32 v4, 0x4f7ffffe, v4
	v_cvt_u32_f32_e32 v4, v4
	v_mul_lo_u32 v1, v3, v4
	v_mul_hi_u32 v1, v4, v1
	v_add_u32_e32 v1, v4, v1
	v_mul_hi_u32 v1, v5, v1
	v_mul_lo_u32 v3, v1, v2
	v_sub_u32_e32 v3, v5, v3
	v_add_u32_e32 v4, 1, v1
	v_cmp_ge_u32_e32 vcc, v3, v2
	s_nop 1
	v_cndmask_b32_e32 v1, v1, v4, vcc
	v_sub_u32_e32 v4, v3, v2
	v_cndmask_b32_e32 v3, v3, v4, vcc
	v_add_u32_e32 v4, 1, v1
	v_cmp_ge_u32_e32 vcc, v3, v2
	v_add_u32_e32 v3, 1, v5
	s_nop 0
	v_cndmask_b32_e32 v1, v1, v4, vcc
	v_mul_lo_u32 v4, v2, v1
	v_add_u32_e32 v2, v4, v2
	v_cmp_ne_u32_e32 vcc, v3, v2
	s_and_saveexec_b64 s[0:1], vcc
	s_xor_b64 s[16:17], exec, s[0:1]
	s_cbranch_execz .LBB0_1081
	buffer_inv sc1
	s_waitcnt lgkmcnt(0)
	v_mov_b32_e32 v0, 0x2000
	global_load_dword v0, v0, s[14:15] offset:1024 sc1
	s_add_u32 s26, s14, 0x2400
	s_addc_u32 s27, s15, 0
	s_waitcnt vmcnt(0)
	v_cmp_eq_u32_e32 vcc, v0, v1
	s_and_saveexec_b64 s[22:23], vcc
	s_cbranch_execz .LBB0_1080
	s_add_u32 s24, s86, 0xe7c1200
	s_addc_u32 s25, s87, 0
	s_mov_b32 s0, 1
	s_mov_b64 s[28:29], 0
	v_mov_b32_e32 v0, 0
	s_branch .LBB0_1071

; DI unsigned xb_ld(unsigned* p) { return __hip_atomic_load(p, __ATOMIC_RELAXED, __HIP_MEMORY_SCOPE_AGENT); }
; DI unsigned xb_add(unsigned* p, unsigned v) { return __hip_atomic_fetch_add(p, v, __ATOMIC_RELAXED, __HIP_MEMORY_SCOPE_AGENT); }
; #define XB_SPIN(cond, bar) do { unsigned _sp = 0; while (cond) { __builtin_amdgcn_s_sleep(1); \
;     if ((++_sp & 255u) == 0u) { if (xb_ld(&(bar)[XB_TMO])) break; if (_sp > XB_SPIN_CAP) { atomicAdd(&(bar)[XB_TMO], 1u); break; } } } } while (0)
; DI void xcd_barrier(const XcdBarrier& b) {
;     ...
;     const unsigned old = xb_add(&bar[XB_XSUB(b.x)], 1u);
;     const unsigned gen = old / nloc;
;     if (old + 1u == (gen + 1u) * nloc) {
;       __builtin_amdgcn_fence(__ATOMIC_RELEASE, "agent");
;       asm volatile("s_waitcnt vmcnt(0)" ::: "memory");
;       const unsigned og = xb_add(&bar[XB_TOP], 1u);
;       const unsigned tg = og / nx;
;       if (og + 1u == (tg + 1u) * nx) xb_add(&bar[XB_TOPGEN], 1u);
;       else XB_SPIN(xb_ld(&bar[XB_TOPGEN]) == tg, bar);
;       __builtin_amdgcn_fence(__ATOMIC_ACQUIRE, "agent");
;       xb_add(&bar[XB_XGEN(b.x)], 1u);
;       asm volatile("s_waitcnt vmcnt(0)" ::: "memory");
;     } else {
;       XB_SPIN(xb_ld(&bar[XB_XGEN(b.x)]) == gen, bar);
.LBB0_1136:
	s_or_b64 exec, exec, s[12:13]
	v_cvt_f32_u32_e32 v4, v2
	s_waitcnt vmcnt(0)
	v_readfirstlane_b32 s0, v3
	v_sub_u32_e32 v3, 0, v2
	v_rcp_iflag_f32_e32 v4, v4
	v_add_u32_e32 v5, s0, v1
	v_mul_f32_e32 v4, 0x4f7ffffe, v4
	v_cvt_u32_f32_e32 v4, v4
	v_mul_lo_u32 v1, v3, v4
	v_mul_hi_u32 v1, v4, v1
	v_add_u32_e32 v1, v4, v1
	v_mul_hi_u32 v1, v5, v1
	v_mul_lo_u32 v3, v1, v2
	v_sub_u32_e32 v3, v5, v3
	v_add_u32_e32 v4, 1, v1
	v_cmp_ge_u32_e32 vcc, v3, v2
	s_nop 1
	v_cndmask_b32_e32 v1, v1, v4, vcc
	v_sub_u32_e32 v4, v3, v2
	v_cndmask_b32_e32 v3, v3, v4, vcc
	v_add_u32_e32 v4, 1, v1
	v_cmp_ge_u32_e32 vcc, v3, v2
	v_add_u32_e32 v3, 1, v5
	s_nop 0
	v_cndmask_b32_e32 v1, v1, v4, vcc
	v_mul_lo_u32 v4, v2, v1
	v_add_u32_e32 v2, v4, v2
	v_cmp_ne_u32_e32 vcc, v3, v2
	s_and_saveexec_b64 s[0:1], vcc
	s_xor_b64 s[10:11], exec, s[0:1]
	s_cbranch_execz .LBB0_1150
	buffer_inv sc1
	s_waitcnt lgkmcnt(0)
	v_mov_b32_e32 v0, 0x2000
	global_load_dword v0, v0, s[8:9] offset:1024 sc1
	s_add_u32 s16, s8, 0x2400
	s_addc_u32 s17, s9, 0
	s_waitcnt vmcnt(0)
	v_cmp_eq_u32_e32 vcc, v0, v1
	s_and_saveexec_b64 s[12:13], vcc
	s_cbranch_execz .LBB0_1149
	s_add_u32 s14, s86, 0xe7c1200
	s_addc_u32 s15, s87, 0
	s_mov_b32 s0, 1
	s_mov_b64 s[22:23], 0
	v_mov_b32_e32 v0, 0
	s_branch .LBB0_1140

; DI unsigned xb_ld(unsigned* p) { return __hip_atomic_load(p, __ATOMIC_RELAXED, __HIP_MEMORY_SCOPE_AGENT); }
; DI unsigned xb_add(unsigned* p, unsigned v) { return __hip_atomic_fetch_add(p, v, __ATOMIC_RELAXED, __HIP_MEMORY_SCOPE_AGENT); }
; #define XB_SPIN(cond, bar) do { unsigned _sp = 0; while (cond) { __builtin_amdgcn_s_sleep(1); \
;     if ((++_sp & 255u) == 0u) { if (xb_ld(&(bar)[XB_TMO])) break; if (_sp > XB_SPIN_CAP) { atomicAdd(&(bar)[XB_TMO], 1u); break; } } } } while (0)
; DI void xcd_barrier(const XcdBarrier& b) {
;     ...
;     const unsigned old = xb_add(&bar[XB_XSUB(b.x)], 1u);
;     const unsigned gen = old / nloc;
;     if (old + 1u == (gen + 1u) * nloc) {
;       __builtin_amdgcn_fence(__ATOMIC_RELEASE, "agent");
;       asm volatile("s_waitcnt vmcnt(0)" ::: "memory");
;       const unsigned og = xb_add(&bar[XB_TOP], 1u);
;       const unsigned tg = og / nx;
;       if (og + 1u == (tg + 1u) * nx) xb_add(&bar[XB_TOPGEN], 1u);
;       else XB_SPIN(xb_ld(&bar[XB_TOPGEN]) == tg, bar);
;       __builtin_amdgcn_fence(__ATOMIC_ACQUIRE, "agent");
;       xb_add(&bar[XB_XGEN(b.x)], 1u);
;       asm volatile("s_waitcnt vmcnt(0)" ::: "memory");
;     } else {
;       XB_SPIN(xb_ld(&bar[XB_XGEN(b.x)]) == gen, bar);
.LBB0_1193:
	s_or_b64 exec, exec, s[10:11]
	v_cvt_f32_u32_e32 v4, v2
	s_waitcnt vmcnt(0)
	v_readfirstlane_b32 s0, v3
	v_sub_u32_e32 v3, 0, v2
	v_rcp_iflag_f32_e32 v4, v4
	v_add_u32_e32 v5, s0, v1
	v_mul_f32_e32 v4, 0x4f7ffffe, v4
	v_cvt_u32_f32_e32 v4, v4
	v_mul_lo_u32 v1, v3, v4
	v_mul_hi_u32 v1, v4, v1
	v_add_u32_e32 v1, v4, v1
	v_mul_hi_u32 v1, v5, v1
	v_mul_lo_u32 v3, v1, v2
	v_sub_u32_e32 v3, v5, v3
	v_add_u32_e32 v4, 1, v1
	v_cmp_ge_u32_e32 vcc, v3, v2
	s_nop 1
	v_cndmask_b32_e32 v1, v1, v4, vcc
	v_sub_u32_e32 v4, v3, v2
	v_cndmask_b32_e32 v3, v3, v4, vcc
	v_add_u32_e32 v4, 1, v1
	v_cmp_ge_u32_e32 vcc, v3, v2
	v_add_u32_e32 v3, 1, v5
	s_nop 0
	v_cndmask_b32_e32 v1, v1, v4, vcc
	v_mul_lo_u32 v4, v2, v1
	v_add_u32_e32 v2, v4, v2
	v_cmp_ne_u32_e32 vcc, v3, v2
	s_and_saveexec_b64 s[0:1], vcc
	s_xor_b64 s[8:9], exec, s[0:1]
	s_cbranch_execz .LBB0_1207
	buffer_inv sc1
	s_waitcnt lgkmcnt(0)
	v_mov_b32_e32 v0, 0x2000
	global_load_dword v0, v0, s[6:7] offset:1024 sc1
	s_add_u32 s14, s6, 0x2400
	s_addc_u32 s15, s7, 0
	s_waitcnt vmcnt(0)
	v_cmp_eq_u32_e32 vcc, v0, v1
	s_and_saveexec_b64 s[10:11], vcc
	s_cbranch_execz .LBB0_1206
	s_add_u32 s12, s86, 0xe7c1200
	s_addc_u32 s13, s87, 0
	s_mov_b32 s0, 1
	s_mov_b64 s[16:17], 0
	v_mov_b32_e32 v0, 0
	s_branch .LBB0_1197

; DI unsigned xb_ld(unsigned* p) { return __hip_atomic_load(p, __ATOMIC_RELAXED, __HIP_MEMORY_SCOPE_AGENT); }
; DI unsigned xb_add(unsigned* p, unsigned v) { return __hip_atomic_fetch_add(p, v, __ATOMIC_RELAXED, __HIP_MEMORY_SCOPE_AGENT); }
; #define XB_SPIN(cond, bar) do { unsigned _sp = 0; while (cond) { __builtin_amdgcn_s_sleep(1); \
;     if ((++_sp & 255u) == 0u) { if (xb_ld(&(bar)[XB_TMO])) break; if (_sp > XB_SPIN_CAP) { atomicAdd(&(bar)[XB_TMO], 1u); break; } } } } while (0)
; DI void xcd_barrier(const XcdBarrier& b) {
;     ...
;     const unsigned old = xb_add(&bar[XB_XSUB(b.x)], 1u);
;     const unsigned gen = old / nloc;
;     if (old + 1u == (gen + 1u) * nloc) {
;       __builtin_amdgcn_fence(__ATOMIC_RELEASE, "agent");
;       asm volatile("s_waitcnt vmcnt(0)" ::: "memory");
;       const unsigned og = xb_add(&bar[XB_TOP], 1u);
;       const unsigned tg = og / nx;
;       if (og + 1u == (tg + 1u) * nx) xb_add(&bar[XB_TOPGEN], 1u);
;       else XB_SPIN(xb_ld(&bar[XB_TOPGEN]) == tg, bar);
;       __builtin_amdgcn_fence(__ATOMIC_ACQUIRE, "agent");
;       xb_add(&bar[XB_XGEN(b.x)], 1u);
;       asm volatile("s_waitcnt vmcnt(0)" ::: "memory");
;     } else {
;       XB_SPIN(xb_ld(&bar[XB_XGEN(b.x)]) == gen, bar);
.LBB0_1376:
	s_or_b64 exec, exec, s[12:13]
	v_cvt_f32_u32_e32 v4, v2
	s_waitcnt vmcnt(0)
	v_readfirstlane_b32 s2, v3
	v_sub_u32_e32 v3, 0, v2
	v_rcp_iflag_f32_e32 v4, v4
	v_add_u32_e32 v5, s2, v1
	v_mul_f32_e32 v4, 0x4f7ffffe, v4
	v_cvt_u32_f32_e32 v4, v4
	v_mul_lo_u32 v1, v3, v4
	v_mul_hi_u32 v1, v4, v1
	v_add_u32_e32 v1, v4, v1
	v_mul_hi_u32 v1, v5, v1
	v_mul_lo_u32 v3, v1, v2
	v_sub_u32_e32 v3, v5, v3
	v_add_u32_e32 v4, 1, v1
	v_cmp_ge_u32_e32 vcc, v3, v2
	s_nop 1
	v_cndmask_b32_e32 v1, v1, v4, vcc
	v_sub_u32_e32 v4, v3, v2
	v_cndmask_b32_e32 v3, v3, v4, vcc
	v_add_u32_e32 v4, 1, v1
	v_cmp_ge_u32_e32 vcc, v3, v2
	v_add_u32_e32 v3, 1, v5
	s_nop 0
	v_cndmask_b32_e32 v1, v1, v4, vcc
	v_mul_lo_u32 v4, v2, v1
	v_add_u32_e32 v2, v4, v2
	v_cmp_ne_u32_e32 vcc, v3, v2
	s_and_saveexec_b64 s[8:9], vcc
	s_xor_b64 s[8:9], exec, s[8:9]
	s_cbranch_execz .LBB0_1390
	buffer_inv sc1
	s_waitcnt lgkmcnt(0)
	v_mov_b32_e32 v0, 0x2000
	global_load_dword v0, v0, s[6:7] offset:1024 sc1
	s_add_u32 s16, s6, 0x2400
	s_addc_u32 s17, s7, 0
	s_waitcnt vmcnt(0)
	v_cmp_eq_u32_e32 vcc, v0, v1
	s_and_saveexec_b64 s[12:13], vcc
	s_cbranch_execz .LBB0_1389
	s_add_u32 s14, s86, 0xe7c1200
	s_addc_u32 s15, s87, 0
	s_mov_b32 s3, 1
	s_mov_b64 s[18:19], 0
	v_mov_b32_e32 v0, 0
	s_branch .LBB0_1380

; DI unsigned xb_ld(unsigned* p) { return __hip_atomic_load(p, __ATOMIC_RELAXED, __HIP_MEMORY_SCOPE_AGENT); }
; DI unsigned xb_add(unsigned* p, unsigned v) { return __hip_atomic_fetch_add(p, v, __ATOMIC_RELAXED, __HIP_MEMORY_SCOPE_AGENT); }
; #define XB_SPIN(cond, bar) do { unsigned _sp = 0; while (cond) { __builtin_amdgcn_s_sleep(1); \
;     if ((++_sp & 255u) == 0u) { if (xb_ld(&(bar)[XB_TMO])) break; if (_sp > XB_SPIN_CAP) { atomicAdd(&(bar)[XB_TMO], 1u); break; } } } } while (0)
; DI void xcd_barrier(const XcdBarrier& b) {
;     ...
;     const unsigned old = xb_add(&bar[XB_XSUB(b.x)], 1u);
;     const unsigned gen = old / nloc;
;     if (old + 1u == (gen + 1u) * nloc) {
;       __builtin_amdgcn_fence(__ATOMIC_RELEASE, "agent");
;       asm volatile("s_waitcnt vmcnt(0)" ::: "memory");
;       const unsigned og = xb_add(&bar[XB_TOP], 1u);
;       const unsigned tg = og / nx;
;       if (og + 1u == (tg + 1u) * nx) xb_add(&bar[XB_TOPGEN], 1u);
;       else XB_SPIN(xb_ld(&bar[XB_TOPGEN]) == tg, bar);
;       __builtin_amdgcn_fence(__ATOMIC_ACQUIRE, "agent");
;       xb_add(&bar[XB_XGEN(b.x)], 1u);
;       asm volatile("s_waitcnt vmcnt(0)" ::: "memory");
;     } else {
;       XB_SPIN(xb_ld(&bar[XB_XGEN(b.x)]) == gen, bar);
.LBB0_1501:
	s_or_b64 exec, exec, s[6:7]
	v_cvt_f32_u32_e32 v4, v2
	s_waitcnt vmcnt(0)
	v_readfirstlane_b32 s4, v3
	v_sub_u32_e32 v3, 0, v2
	v_rcp_iflag_f32_e32 v4, v4
	v_add_u32_e32 v5, s4, v1
	v_mul_f32_e32 v4, 0x4f7ffffe, v4
	v_cvt_u32_f32_e32 v4, v4
	v_mul_lo_u32 v1, v3, v4
	v_mul_hi_u32 v1, v4, v1
	v_add_u32_e32 v1, v4, v1
	v_mul_hi_u32 v1, v5, v1
	v_mul_lo_u32 v3, v1, v2
	v_sub_u32_e32 v3, v5, v3
	v_add_u32_e32 v4, 1, v1
	v_cmp_ge_u32_e32 vcc, v3, v2
	s_nop 1
	v_cndmask_b32_e32 v1, v1, v4, vcc
	v_sub_u32_e32 v4, v3, v2
	v_cndmask_b32_e32 v3, v3, v4, vcc
	v_add_u32_e32 v4, 1, v1
	v_cmp_ge_u32_e32 vcc, v3, v2
	v_add_u32_e32 v3, 1, v5
	s_nop 0
	v_cndmask_b32_e32 v1, v1, v4, vcc
	v_mul_lo_u32 v4, v2, v1
	v_add_u32_e32 v2, v4, v2
	v_cmp_ne_u32_e32 vcc, v3, v2
	s_and_saveexec_b64 s[4:5], vcc
	s_xor_b64 s[4:5], exec, s[4:5]
	s_cbranch_execz .LBB0_1515
	buffer_inv sc1
	s_waitcnt lgkmcnt(0)
	v_mov_b32_e32 v0, 0x2000
	global_load_dword v0, v0, s[0:1] offset:1024 sc1
	s_add_u32 s10, s0, 0x2400
	s_addc_u32 s11, s1, 0
	s_waitcnt vmcnt(0)
	v_cmp_eq_u32_e32 vcc, v0, v1
	s_and_saveexec_b64 s[6:7], vcc
	s_cbranch_execz .LBB0_1514
	s_add_u32 s8, s86, 0xe7c1200
	s_addc_u32 s9, s87, 0
	s_mov_b32 s22, 1
	s_mov_b64 s[12:13], 0
	v_mov_b32_e32 v0, 0
	s_branch .LBB0_1505
